# attention QK: K-fragment reads in consumption order with counted lgkmcnt(4) waits instead of lgkmcnt(0) every 3 groups (on lean-softmax v26b)
# baseline (speedup 1.0000x reference)
; #define LAS __attribute__((address_space(3)))
; __device__ __forceinline__ void att_qk_sm(const LAS unsigned char* kb, int klane, const bf16x8 (&qf)[12], f32x16 (&o)[4], float& mrun, float& lrun, bf16x8 (&pb)[4]) {
;     constexpr int KP = 400;
;     f32x16 s0, s1;
; #pragma unroll
;     for (int i = 0; i < 16; ++i) { s0[i] = 0.f; s1[i] = 0.f; }
;     bf16x8 ka[3][2];
; #pragma unroll
;     for (int g = 0; g < 2; ++g) { ka[g][0] = *(const LAS bf16x8*)(kb + klane + g * 32); ka[g][1] = *(const LAS bf16x8*)(kb + klane + 32 * KP + g * 32); }
; #pragma unroll
;     for (int g = 0; g < 12; ++g) {
;         if (g < 10) { ka[(g + 2) % 3][0] = *(const LAS bf16x8*)(kb + klane + (g + 2) * 32); ka[(g + 2) % 3][1] = *(const LAS bf16x8*)(kb + klane + 32 * KP + (g + 2) * 32); }
;         __builtin_amdgcn_sched_barrier(0);
;         s0 = __builtin_amdgcn_mfma_f32_32x32x16_bf16(ka[g % 3][0], qf[g], s0, 0, 0, 0);
;         s1 = __builtin_amdgcn_mfma_f32_32x32x16_bf16(ka[g % 3][1], qf[g], s1, 0, 0, 0);
;         __builtin_amdgcn_sched_barrier(0);
;     }
.LBB0_1018:
	s_cmp_gt_u32 s16, s6
	s_cselect_b64 s[16:17], -1, 0
	s_and_b64 vcc, exec, s[16:17]
	s_mul_i32 s61, s58, 0xb400
	s_cbranch_vccnz .Latt_skipq
	v_add_u32_e32 v194, s74, v223
	ds_read_b128 v[64:67], v194
	ds_read_b128 v[68:71], v194 offset:12800
	ds_read_b128 v[170:173], v194 offset:32
	ds_read_b128 v[174:177], v194 offset:12832
	ds_read_b128 v[182:185], v194 offset:64
	ds_read_b128 v[178:181], v194 offset:12864
	s_waitcnt lgkmcnt(4)
	v_mfma_f32_32x32x16_bf16 v[80:95], v[64:67], v[96:99], 0
	v_mfma_f32_32x32x16_bf16 v[64:79], v[68:71], v[96:99], 0
	ds_read_b128 v[186:189], v194 offset:96
	ds_read_b128 v[190:193], v194 offset:12896
	s_waitcnt lgkmcnt(4)
	v_mfma_f32_32x32x16_bf16 v[80:95], v[170:173], v[100:103], v[80:95]
	v_mfma_f32_32x32x16_bf16 v[64:79], v[174:177], v[100:103], v[64:79]
	ds_read_b128 v[170:173], v194 offset:128
	ds_read_b128 v[174:177], v194 offset:12928
	s_waitcnt lgkmcnt(4)
	v_mfma_f32_32x32x16_bf16 v[80:95], v[182:185], v[104:107], v[80:95]
	v_mfma_f32_32x32x16_bf16 v[64:79], v[178:181], v[104:107], v[64:79]
	ds_read_b128 v[178:181], v194 offset:160
	ds_read_b128 v[182:185], v194 offset:12960
	s_waitcnt lgkmcnt(4)
	v_mfma_f32_32x32x16_bf16 v[80:95], v[186:189], v[108:111], v[80:95]
	v_mfma_f32_32x32x16_bf16 v[64:79], v[190:193], v[108:111], v[64:79]
	ds_read_b128 v[186:189], v194 offset:192
	ds_read_b128 v[190:193], v194 offset:12992
	s_waitcnt lgkmcnt(4)
	v_mfma_f32_32x32x16_bf16 v[80:95], v[170:173], v[112:115], v[80:95]
	v_mfma_f32_32x32x16_bf16 v[64:79], v[174:177], v[112:115], v[64:79]
	ds_read_b128 v[170:173], v194 offset:224
	ds_read_b128 v[174:177], v194 offset:13024
	s_waitcnt lgkmcnt(4)
	v_mfma_f32_32x32x16_bf16 v[80:95], v[178:181], v[116:119], v[80:95]
	v_mfma_f32_32x32x16_bf16 v[64:79], v[182:185], v[116:119], v[64:79]
	ds_read_b128 v[178:181], v194 offset:256
	ds_read_b128 v[182:185], v194 offset:13056
	s_waitcnt lgkmcnt(4)
	v_mfma_f32_32x32x16_bf16 v[80:95], v[186:189], v[120:123], v[80:95]
	v_mfma_f32_32x32x16_bf16 v[64:79], v[190:193], v[120:123], v[64:79]
	ds_read_b128 v[186:189], v194 offset:288
	ds_read_b128 v[190:193], v194 offset:13088
	s_waitcnt lgkmcnt(4)
	v_mfma_f32_32x32x16_bf16 v[80:95], v[170:173], v[124:127], v[80:95]
	v_mfma_f32_32x32x16_bf16 v[64:79], v[174:177], v[124:127], v[64:79]
	ds_read_b128 v[170:173], v194 offset:320
	ds_read_b128 v[174:177], v194 offset:13120
	s_waitcnt lgkmcnt(4)
	v_mfma_f32_32x32x16_bf16 v[80:95], v[178:181], v[128:131], v[80:95]
	v_mfma_f32_32x32x16_bf16 v[64:79], v[182:185], v[128:131], v[64:79]
	ds_read_b128 v[178:181], v194 offset:352
	ds_read_b128 v[182:185], v194 offset:13152
	s_waitcnt lgkmcnt(4)
	v_mfma_f32_32x32x16_bf16 v[80:95], v[186:189], v[132:135], v[80:95]
	v_mfma_f32_32x32x16_bf16 v[64:79], v[190:193], v[132:135], v[64:79]
	s_waitcnt lgkmcnt(2)
	v_mfma_f32_32x32x16_bf16 v[80:95], v[170:173], v[136:139], v[80:95]
	v_mfma_f32_32x32x16_bf16 v[64:79], v[174:177], v[136:139], v[64:79]
	s_waitcnt lgkmcnt(0)
	v_mfma_f32_32x32x16_bf16 v[80:95], v[178:181], v[140:143], v[80:95]
	v_mfma_f32_32x32x16_bf16 v[64:79], v[182:185], v[140:143], v[64:79]
	s_cmp_lg_u32 s83, 0
	s_cbranch_scc0 .Latt_noissue_q
	s_mov_b64 s[4:5], s[10:11]
	s_cmp_eq_u32 s33, 0
	s_cselect_b32 s82, s76, s80
	s_add_i32 m0, s76, s19
	v_lshl_add_u64 v[172:173], s[4:5], 0, v[144:145]
	global_load_lds_dwordx4 v[172:173], off
	s_add_i32 m0, s76, s20
	v_lshl_add_u64 v[172:173], s[4:5], 0, v[146:147]
	global_load_lds_dwordx4 v[172:173], off
	s_add_i32 m0, s76, s21
	v_lshl_add_u64 v[172:173], s[4:5], 0, v[148:149]
	global_load_lds_dwordx4 v[172:173], off
	s_add_i32 m0, s82, s22
	v_lshl_add_u64 v[172:173], s[4:5], 0, v[150:151]
	global_load_lds_dwordx4 v[172:173], off
	s_add_i32 m0, s80, s23
	v_lshl_add_u64 v[172:173], s[4:5], 0, v[156:157]
	global_load_lds_dwordx4 v[172:173], off
	s_add_i32 m0, s80, s24
	v_lshl_add_u64 v[172:173], s[4:5], 0, v[154:155]
	global_load_lds_dwordx4 v[172:173], off
	s_branch .Latt_issued_q
